# attention: QK addresses from one persistent per-lane constant (4 VALU), far exp args via v_pk_fma_f32, direct far/active branches; FFN-up K-loop head wait removed
# baseline (speedup 1.0000x reference)
.LBB0_2728:
	s_add_u32 s2, s4, s0
	s_addc_u32 s3, s5, s1
	global_load_dwordx4 v[4:7], v1, s[2:3]
	global_load_dwordx4 v[8:11], v1, s[2:3] offset:16
	s_add_u32 s2, s6, s0
	s_addc_u32 s3, s7, s1
	global_load_dwordx4 v[12:15], v1, s[2:3]
	global_load_dwordx4 v[16:19], v1, s[2:3] offset:16
	s_add_u32 s2, s8, s0
	s_addc_u32 s3, s9, s1
	global_load_dwordx4 v[20:23], v1, s[2:3]
	global_load_dwordx4 v[24:27], v1, s[2:3] offset:16
	s_add_u32 s2, s10, s0
	s_addc_u32 s3, s11, s1
	global_load_dwordx4 v[28:31], v1, s[2:3]
	global_load_dwordx4 v[32:35], v1, s[2:3] offset:16
	s_add_u32 s0, s0, 32
	s_addc_u32 s1, s1, 0
	s_cmpk_lg_i32 s0, 0x200
	s_waitcnt vmcnt(7)
	v_mov_b32_e32 v37, v4
	v_mov_b32_e32 v39, v6
	s_waitcnt vmcnt(6)
	v_mov_b32_e32 v41, v8
	s_waitcnt vmcnt(5)
	v_mov_b32_e32 v45, v12
	v_mov_b32_e32 v47, v14
	s_waitcnt vmcnt(4)
	v_mov_b32_e32 v49, v16
	s_waitcnt vmcnt(3)
	v_mov_b32_e32 v36, v20
	v_mov_b32_e32 v4, v21
	v_mov_b32_e32 v38, v22
	s_waitcnt vmcnt(1)
	v_mov_b32_e32 v44, v28
	v_mov_b32_e32 v12, v29
	v_pk_fma_f32 v[2:3], v[36:37], v[44:45], v[2:3]
	v_mov_b32_e32 v46, v30
	v_pk_fma_f32 v[2:3], v[4:5], v[12:13], v[2:3]
	v_mov_b32_e32 v6, v23
	v_mov_b32_e32 v14, v31
	v_pk_fma_f32 v[2:3], v[38:39], v[46:47], v[2:3]
	v_mov_b32_e32 v40, v24
	s_waitcnt vmcnt(0)
	v_mov_b32_e32 v48, v32
	v_pk_fma_f32 v[2:3], v[6:7], v[14:15], v[2:3]
	v_mov_b32_e32 v8, v25
	v_mov_b32_e32 v16, v33
	v_pk_fma_f32 v[2:3], v[40:41], v[48:49], v[2:3]
	v_mov_b32_e32 v43, v10
	v_mov_b32_e32 v51, v18
	v_mov_b32_e32 v42, v26
	v_mov_b32_e32 v50, v34
	v_pk_fma_f32 v[2:3], v[8:9], v[16:17], v[2:3]
	v_mov_b32_e32 v10, v27
	v_mov_b32_e32 v18, v35
	v_pk_fma_f32 v[2:3], v[42:43], v[50:51], v[2:3]
	s_nop 0
	v_pk_fma_f32 v[2:3], v[10:11], v[18:19], v[2:3]
	s_cbranch_scc1 .LBB0_2728
	s_add_u32 s0, s92, 0x30d00000
	v_writelane_b32 v255, s0, 20
	s_addc_u32 s0, s93, 0
	v_writelane_b32 v255, s0, 6
	s_getreg_b32 s0, hwreg(HW_REG_XCC_ID, 0, 4)
	s_and_b32 s0, s0, 15
	s_add_u32 s2, s92, 0x34e00000
	s_addc_u32 s3, s93, 0
	v_writelane_b32 v254, s2, 3
	v_writelane_b32 v255, s0, 10
	s_add_u32 s55, s92, 0x38f00000
	v_writelane_b32 v254, s3, 4
	v_writelane_b32 v255, s92, 21
	v_readlane_b32 s7, v254, 0
	s_addc_u32 s95, s93, 0
	s_lshr_b32 s2, s7, 7
	s_bfe_u32 s3, s7, 0x10006
	s_lshl_b32 s46, s2, 5
	s_cmpk_lt_u32 s7, 0x200
	v_readlane_b32 s8, v254, 28
	s_cselect_b64 s[56:57], -1, 0
	s_lshl_b32 s5, s8, 5
	v_writelane_b32 v255, s93, 22
	s_and_b32 s5, s5, 0x7fffff80
	v_mul_f32_e32 v1, 0x3fb8aa3b, v3
	v_mul_f32_e32 v2, 0x3fb8aa3b, v2
	s_lshl_b32 s4, s8, 2
	v_writelane_b32 v255, s5, 11
	s_lshl_b32 s5, s8, 4
	v_exp_f32_e32 v1, v1
	v_exp_f32_e32 v2, v2
	s_and_b32 s80, s5, 48
	s_or_b32 s5, s4, 1
	s_lshl_b32 s81, s8, 12
	s_lshl_b32 s6, s5, 2
	s_lshl_b32 s83, s5, 10
	s_or_b32 s5, s4, 2
	s_or_b32 s4, s4, 3
	s_lshl_b32 s85, s3, 7
	s_and_b32 s82, s6, 52
	s_lshl_b32 s6, s5, 2
	s_lshl_b32 s87, s5, 10
	s_lshl_b32 s5, s4, 2
	s_add_i32 s97, s81, 0
	s_lshl_b32 s3, s3, 14
	s_and_b32 s86, s6, 56
	s_and_b32 s90, s5, 60
	s_lshl_b32 s91, s4, 10
	s_lshl_b32 s96, s8, 3
	s_add_i32 s42, s97, 0x10000
	s_add_i32 s43, s3, 0
	v_sub_f32_e32 v1, v1, v2
	s_bitcmp1_b32 s7, 6
	v_add_f32_e32 v1, 0x3eb60549, v1
	s_cselect_b64 s[6:7], -1, 0
	s_lshl_b32 s2, s2, 15
	s_add_i32 s92, 0, 0x26c40
	v_mbcnt_lo_u32_b32 v2, -1, 0
	s_mov_b32 s45, 0
	v_cmp_eq_u32_e64 s[0:1], 0, v0
	v_cndmask_b32_e64 v1, 1.0, v1, s[6:7]
	s_add_i32 s33, s2, 0
	s_sub_i32 s47, 0, s46
	s_add_i32 s54, s96, 64
	v_mov_b32_e32 v3, 0
	s_movk_i32 s93, 0xff00
	v_cndmask_b32_e64 v243, 0, 1, s[56:57]
	s_mov_b64 s[58:59], 0x80
	s_mov_b64 s[52:53], 0x100
	s_mov_b64 s[48:49], 0x180
	s_movk_i32 s88, 0x80
	s_movk_i32 s89, 0xfee0
	s_mov_b32 s94, 0x3b800000
	s_mov_b32 s84, 0x800000
	v_mov_b32_e32 v245, s92
	v_lshrrev_b32_e32 v4, 5, v242
	v_lshlrev_b32_e32 v4, 4, v4
	v_lshlrev_b32_e32 v5, 4, v242
	v_and_b32_e32 v5, 0x70, v5
	v_xor_b32_e32 v4, v4, v5
	v_and_b32_e32 v5, 31, v242
	v_lshl_or_b32 v246, v5, 8, v4
	v_mov_b32_e32 v247, 0xdf
	v_mov_b32_e32 v248, 0xf149f2ca
	v_mbcnt_hi_u32_b32 v249, -1, v2
	v_mov_b32_e32 v244, 0x3727c5ac
	s_mov_b32 s3, 0
	s_mov_b32 s32, 0x20800
	v_lshrrev_b32_e32 v4, 4, v242
	v_and_b32_e32 v5, 15, v242
	v_xor_b32_e32 v5, v5, v4
	v_lshlrev_b32_e32 v5, 4, v5
	v_lshl_add_u32 v4, v4, 12, v5
	v_xor_b32_e32 v5, 64, v4
	v_add_u32_e32 v5, 0x4000, v5
	v_add_u32_e32 v6, 0x8000, v4
	v_add_u32_e32 v7, 0x8000, v5
	v_bfe_u32 v8, v242, 2, 3
	v_and_b32_e32 v9, 3, v242
	v_lshlrev_b32_e32 v9, 4, v9
	v_lshl_add_u32 v8, v8, 12, v9
	v_and_b32_e32 v9, 32, v242
	v_lshl_add_u32 v8, v9, 1, v8
	v_add_u32_e32 v9, 0x80, v8
	v_add_u32_e32 v10, 0x100, v8
	v_add_u32_e32 v11, 0x180, v8
	v_lshl_add_u32 v12, v242, 5, s32
	ds_write_b128 v12, v[4:7]
	ds_write_b128 v12, v[8:11] offset:16
	s_waitcnt lgkmcnt(0)
	s_branch .LBB0_2731

.LBB0_2761:
	s_cmp_le_i32 s19, s17
	s_cselect_b64 s[8:9], -1, 0
	s_and_b64 s[10:11], s[56:57], s[8:9]
	s_and_b64 vcc, exec, s[10:11]
	s_cbranch_vccnz .Lat_active
	s_add_i32 s10, s19, 1
	s_cmp_ge_i32 s10, s16
	s_cbranch_scc1 .LBB0_2764
	v_mov_b32_e32 v8, v242
	s_add_i32 s11, s80, s20
	v_ashrrev_i32_e32 v9, 4, v8
	v_add_u32_e32 v11, s11, v9
	v_add_u32_e32 v4, 64, v11
	v_min_i32_e32 v4, s14, v4
	v_and_b32_e32 v10, 15, v8
	s_add_i32 s8, s21, 0x8000
	v_ashrrev_i32_e32 v5, 31, v4
	s_and_b32 s8, s8, 0x8000
	v_bitop3_b32 v2, v9, v10, 7 bitop3:0x6c
	v_lshlrev_b64 v[4:5], 12, v[4:5]
	s_add_i32 s9, s8, 0
	v_lshl_add_u64 v[4:5], s[2:3], 0, v[4:5]
	v_lshlrev_b32_e32 v2, 4, v2
	v_lshl_add_u64 v[4:5], v[4:5], 0, v[2:3]
	s_add_i32 m0, s9, s81
	v_mov_b32_e32 v7, v3
	global_load_lds_dwordx4 v[4:5], off
	v_add_u32_e32 v4, s82, v9
	v_bitop3_b32 v6, v4, v10, 7 bitop3:0x6c
	v_add_u32_e32 v4, 0x44, v11
	v_min_i32_e32 v4, s14, v4
	v_ashrrev_i32_e32 v5, 31, v4
	v_lshlrev_b64 v[4:5], 12, v[4:5]
	v_lshl_add_u64 v[4:5], s[2:3], 0, v[4:5]
	v_lshlrev_b32_e32 v6, 4, v6
	v_lshl_add_u64 v[4:5], v[4:5], 0, v[6:7]
	s_add_i32 m0, s9, s83
	s_add_i32 s8, s42, s8
	global_load_lds_dwordx4 v[4:5], off
	v_add_u32_e32 v4, 0x48, v11
	v_min_i32_e32 v4, s14, v4
	v_ashrrev_i32_e32 v5, 31, v4
	v_lshlrev_b64 v[4:5], 12, v[4:5]
	v_lshl_add_u64 v[4:5], s[2:3], 0, v[4:5]
	v_lshl_add_u64 v[4:5], v[4:5], 0, v[2:3]
	s_add_i32 m0, s9, s87
	v_add_u32_e32 v2, s90, v9
	global_load_lds_dwordx4 v[4:5], off
	v_add_u32_e32 v4, 0x4c, v11
	v_min_i32_e32 v4, s14, v4
	v_ashrrev_i32_e32 v5, 31, v4
	v_bitop3_b32 v2, v2, v10, 7 bitop3:0x6c
	v_lshlrev_b64 v[4:5], 12, v[4:5]
	v_lshl_add_u64 v[4:5], s[2:3], 0, v[4:5]
	v_lshlrev_b32_e32 v2, 4, v2
	v_lshl_add_u64 v[4:5], v[4:5], 0, v[2:3]
	s_add_i32 m0, s9, s91
	v_bfe_u32 v2, v8, 2, 3
	s_add_i32 s9, s54, s20
	v_add_u32_e32 v2, s9, v2
	v_min_i32_e32 v6, s14, v2
	global_load_lds_dwordx4 v[4:5], off
	v_and_b32_e32 v4, 0xffffffe0, v8
	v_lshlrev_b32_e32 v5, 3, v8
	v_ashrrev_i32_e32 v7, 31, v6
	v_and_or_b32 v4, v5, 24, v4
	v_lshlrev_b64 v[6:7], 12, v[6:7]
	v_lshl_add_u64 v[6:7], s[4:5], 0, v[6:7]
	v_ashrrev_i32_e32 v5, 31, v4
	v_lshl_add_u64 v[4:5], v[4:5], 1, v[6:7]
	s_mov_b32 m0, s8
	v_lshl_add_u64 v[6:7], v[4:5], 0, s[58:59]
	global_load_lds_dwordx4 v[4:5], off
	s_add_i32 m0, s8, 0x400
	s_nop 0
	global_load_lds_dwordx4 v[6:7], off
	v_lshl_add_u64 v[6:7], v[4:5], 0, s[52:53]
	s_add_i32 m0, s8, 0x800
	v_lshl_add_u64 v[4:5], v[4:5], 0, s[48:49]
	global_load_lds_dwordx4 v[6:7], off
	s_add_i32 m0, s8, 0xc00
	s_nop 0
	global_load_lds_dwordx4 v[4:5], off

.Lat_active:
	s_add_i32 s10, s19, 1
	s_cmp_ge_i32 s10, s16
	s_cbranch_scc1 .Lat_nodma
	s_add_i32 s10, s80, s20
	s_add_i32 s10, s10, 64
	s_lshl_b32 s10, s10, 12
	s_add_u32 s98, s2, s10
	s_addc_u32 s99, s3, 0
	s_add_i32 s8, s21, 0x8000
	s_and_b32 s8, s8, 0x8000
	s_add_i32 s9, s8, 0
	s_add_i32 m0, s9, s81
	s_add_i32 s10, s54, s20
	global_load_lds_dwordx4 v200, s[98:99]
	s_add_i32 m0, s9, s83
	s_lshl_b32 s10, s10, 12
	global_load_lds_dwordx4 v201, s[98:99]
	s_add_i32 m0, s9, s87
	s_add_i32 s8, s42, s8
	global_load_lds_dwordx4 v202, s[98:99]
	s_add_i32 m0, s9, s91
	s_nop 0
	global_load_lds_dwordx4 v203, s[98:99]
	s_add_u32 s98, s4, s10
	s_addc_u32 s99, s5, 0
	s_mov_b32 m0, s8
	s_nop 0
	global_load_lds_dwordx4 v204, s[98:99]
	s_add_i32 m0, s8, 0x400
	s_nop 0
	global_load_lds_dwordx4 v205, s[98:99]
	s_add_i32 m0, s8, 0x800
	s_nop 0
	global_load_lds_dwordx4 v206, s[98:99]
	s_add_i32 m0, s8, 0xc00
	s_nop 0
	global_load_lds_dwordx4 v207, s[98:99]
.Lat_nodma:
	s_and_b32 s22, s21, 0x8000
	s_add_i32 s8, s43, s22
	v_add_u32_e32 v192, s8, v246
	ds_read_b128 v[4:7], v192
	ds_read_b128 v[8:11], v192 offset:8192
	v_xor_b32_e32 v193, 32, v192
	ds_read_b128 v[12:15], v193
	ds_read_b128 v[178:181], v193 offset:8192
	v_xor_b32_e32 v194, 64, v192
	ds_read_b128 v[182:185], v194
	ds_read_b128 v[186:189], v194 offset:8192
	v_xor_b32_e32 v195, 0x60, v192
	s_waitcnt lgkmcnt(0)
	v_mfma_f32_32x32x16_bf16 v[162:177], v[4:7], v[210:213], 0
	v_mfma_f32_32x32x16_bf16 v[146:161], v[8:11], v[210:213], 0
	ds_read_b128 v[4:7], v195
	ds_read_b128 v[8:11], v195 offset:8192
	v_mfma_f32_32x32x16_bf16 v[162:177], v[12:15], v[214:217], v[162:177]
	v_mfma_f32_32x32x16_bf16 v[146:161], v[178:181], v[214:217], v[146:161]
	ds_read_b128 v[12:15], v192 offset:128
	ds_read_b128 v[178:181], v192 offset:8320
	v_mfma_f32_32x32x16_bf16 v[162:177], v[182:185], v[218:221], v[162:177]
	v_mfma_f32_32x32x16_bf16 v[146:161], v[186:189], v[218:221], v[146:161]
	ds_read_b128 v[182:185], v193 offset:128
	ds_read_b128 v[186:189], v193 offset:8320
	s_waitcnt lgkmcnt(0)
	v_mfma_f32_32x32x16_bf16 v[162:177], v[4:7], v[222:225], v[162:177]
	v_mfma_f32_32x32x16_bf16 v[146:161], v[8:11], v[222:225], v[146:161]
	ds_read_b128 v[4:7], v194 offset:128
	ds_read_b128 v[8:11], v194 offset:8320
	v_mfma_f32_32x32x16_bf16 v[162:177], v[12:15], v[226:229], v[162:177]
	v_mfma_f32_32x32x16_bf16 v[146:161], v[178:181], v[226:229], v[146:161]
	ds_read_b128 v[12:15], v195 offset:128
	ds_read_b128 v[178:181], v195 offset:8320
	v_mfma_f32_32x32x16_bf16 v[162:177], v[182:185], v[230:233], v[162:177]
	v_mfma_f32_32x32x16_bf16 v[146:161], v[186:189], v[230:233], v[146:161]
	s_waitcnt lgkmcnt(0)
	v_mfma_f32_32x32x16_bf16 v[162:177], v[4:7], v[234:237], v[162:177]
	v_mfma_f32_32x32x16_bf16 v[146:161], v[8:11], v[234:237], v[146:161]
	v_mfma_f32_32x32x16_bf16 v[162:177], v[12:15], v[238:241], v[162:177]
	v_mfma_f32_32x32x16_bf16 v[146:161], v[178:181], v[238:241], v[146:161]
	s_add_i32 s23, s18, s20
	s_add_i32 s10, s20, 63
	s_add_i32 s8, s23, 0xffffe0bf
	s_cmpk_lt_i32 s8, 0xffa6
	s_cselect_b64 s[8:9], -1, 0
	s_cmp_lt_i32 s10, s15
	s_cselect_b64 s[12:13], -1, 0
	s_and_b64 s[10:11], s[12:13], s[8:9]
	s_and_b64 vcc, exec, s[10:11]
	s_cbranch_vccnz .Lat_farmax
	v_lshrrev_b32_e32 v11, 3, v242
	v_and_b32_e32 v11, 4, v11
	v_and_b32_e32 v2, 31, v242
	v_sub_u32_e32 v2, v11, v2
	v_add_u32_e32 v2, s23, v2
	s_add_i32 s23, 0, 0x18600
	v_lshl_add_u32 v2, v2, 2, s23
	ds_read2_b32 v[178:179], v2 offset0:0 offset1:1
	ds_read2_b32 v[180:181], v2 offset0:2 offset1:3
	ds_read2_b32 v[182:183], v2 offset0:8 offset1:9
	ds_read2_b32 v[184:185], v2 offset0:10 offset1:11
	ds_read2_b32 v[186:187], v2 offset0:16 offset1:17
	ds_read2_b32 v[188:189], v2 offset0:18 offset1:19
	ds_read2_b32 v[190:191], v2 offset0:24 offset1:25
	ds_read2_b32 v[192:193], v2 offset0:26 offset1:27
	ds_read2_b32 v[194:195], v2 offset0:32 offset1:33
	ds_read2_b32 v[196:197], v2 offset0:34 offset1:35
	ds_read2_b32 v[198:199], v2 offset0:40 offset1:41
	ds_read2_b32 v[200:201], v2 offset0:42 offset1:43
	ds_read2_b32 v[202:203], v2 offset0:48 offset1:49
	ds_read2_b32 v[204:205], v2 offset0:50 offset1:51
	ds_read2_b32 v[206:207], v2 offset0:56 offset1:57
	ds_read2_b32 v[208:209], v2 offset0:58 offset1:59
	s_waitcnt lgkmcnt(0)
	v_fmamk_f32 v162, v162, 0x3e0293ee, v178
	v_fmamk_f32 v146, v146, 0x3e0293ee, v194
	v_fmamk_f32 v163, v163, 0x3e0293ee, v179
	v_fmamk_f32 v147, v147, 0x3e0293ee, v195
	v_max_f32_e32 v2, v162, v146
	v_fmamk_f32 v164, v164, 0x3e0293ee, v180
	v_fmamk_f32 v148, v148, 0x3e0293ee, v196
	v_max3_f32 v2, v2, v163, v147
	v_fmamk_f32 v165, v165, 0x3e0293ee, v181
	v_fmamk_f32 v149, v149, 0x3e0293ee, v197
	v_max3_f32 v2, v2, v164, v148
	v_fmamk_f32 v166, v166, 0x3e0293ee, v182
	v_fmamk_f32 v150, v150, 0x3e0293ee, v198
	v_max3_f32 v2, v2, v165, v149
	v_fmamk_f32 v167, v167, 0x3e0293ee, v183
	v_fmamk_f32 v151, v151, 0x3e0293ee, v199
	v_max3_f32 v2, v2, v166, v150
	v_fmamk_f32 v168, v168, 0x3e0293ee, v184
	v_fmamk_f32 v152, v152, 0x3e0293ee, v200
	v_max3_f32 v2, v2, v167, v151
	v_fmamk_f32 v169, v169, 0x3e0293ee, v185
	v_fmamk_f32 v153, v153, 0x3e0293ee, v201
	v_max3_f32 v2, v2, v168, v152
	v_fmamk_f32 v170, v170, 0x3e0293ee, v186
	v_fmamk_f32 v154, v154, 0x3e0293ee, v202
	v_max3_f32 v2, v2, v169, v153
	v_fmamk_f32 v171, v171, 0x3e0293ee, v187
	v_fmamk_f32 v155, v155, 0x3e0293ee, v203
	v_max3_f32 v2, v2, v170, v154
	v_fmamk_f32 v172, v172, 0x3e0293ee, v188
	v_fmamk_f32 v156, v156, 0x3e0293ee, v204
	v_max3_f32 v2, v2, v171, v155
	v_fmamk_f32 v173, v173, 0x3e0293ee, v189
	v_fmamk_f32 v157, v157, 0x3e0293ee, v205
	v_max3_f32 v2, v2, v172, v156
	v_fmamk_f32 v174, v174, 0x3e0293ee, v190
	v_fmamk_f32 v158, v158, 0x3e0293ee, v206
	v_max3_f32 v2, v2, v173, v157
	v_fmamk_f32 v175, v175, 0x3e0293ee, v191
	v_fmamk_f32 v159, v159, 0x3e0293ee, v207
	v_max3_f32 v2, v2, v174, v158
	v_fmamk_f32 v176, v176, 0x3e0293ee, v192
	v_fmamk_f32 v160, v160, 0x3e0293ee, v208
	v_max3_f32 v2, v2, v175, v159
	v_fmamk_f32 v177, v177, 0x3e0293ee, v193
	v_fmamk_f32 v161, v161, 0x3e0293ee, v209
	v_max3_f32 v2, v2, v176, v160
	v_max3_f32 v4, v2, v177, v161
	s_branch .LBB0_2770
.Lat_farmax:
	v_max_f32_e32 v4, v162, v146
	v_max3_f32 v4, v4, v163, v147
	v_max3_f32 v4, v4, v164, v148
	v_max3_f32 v4, v4, v165, v149
	v_max3_f32 v4, v4, v166, v150
	v_max3_f32 v4, v4, v167, v151
	v_max3_f32 v4, v4, v168, v152
	v_max3_f32 v4, v4, v169, v153
	v_max3_f32 v4, v4, v170, v154
	v_max3_f32 v4, v4, v171, v155
	v_max3_f32 v4, v4, v172, v156
	v_max3_f32 v4, v4, v173, v157
	v_max3_f32 v4, v4, v174, v158
	v_max3_f32 v4, v4, v175, v159
	v_max3_f32 v4, v4, v176, v160
	v_max3_f32 v4, v4, v177, v161
	v_fmamk_f32 v4, v4, 0x3e0293ee, v253
.LBB0_2770:
	v_mov_b32_e32 v5, v4
	s_mov_b32 s8, 0x40c00000
	s_nop 0
	v_permlane32_swap_b32_e32 v5, v4
	v_max_f32_e32 v4, v4, v5
	v_sub_f32_e32 v5, v4, v251
	v_cmp_lt_f32_e32 vcc, s8, v5
	s_cbranch_vccz .LBB0_2772
	v_lshrrev_b32_e32 v11, 3, v242
	v_and_b32_e32 v11, 4, v11
	v_and_b32_e32 v13, 64, v249
	v_max_f32_e32 v4, v4, v4
	v_max_f32_e32 v5, v251, v251
	v_max_f32_e32 v180, v5, v4
	v_sub_f32_e32 v4, v251, v180
	v_add_u32_e32 v12, 11, v11
	v_add_u32_e32 v14, 17, v11
	v_exp_f32_e32 v181, v4
	v_and_or_b32 v12, v12, 63, v13
	v_and_or_b32 v14, v14, 61, v13
	v_and_or_b32 v4, v11, 60, v13
	v_add_u32_e32 v8, 8, v11
	v_add_u32_e32 v9, 9, v11
	v_add_u32_e32 v10, 10, v11
	v_lshlrev_b32_e32 v182, 2, v12
	v_add_u32_e32 v12, 16, v11
	v_lshlrev_b32_e32 v183, 2, v14
	v_add_u32_e32 v14, 18, v11
	v_add_u32_e32 v15, 19, v11
	v_add_u32_e32 v16, 24, v11
	v_add_u32_e32 v17, 25, v11
	v_add_u32_e32 v178, 26, v11
	v_add_u32_e32 v11, 27, v11
	v_and_or_b32 v8, v8, 60, v13
	v_and_or_b32 v9, v9, 61, v13
	v_and_or_b32 v10, v10, 62, v13
	v_and_or_b32 v12, v12, 60, v13
	v_and_or_b32 v14, v14, 62, v13
	v_and_or_b32 v15, v15, 63, v13
	v_and_or_b32 v16, v16, 60, v13
	v_and_or_b32 v17, v17, 61, v13
	v_and_or_b32 v178, v178, 62, v13
	v_and_or_b32 v11, v11, 63, v13
	v_lshlrev_b32_e32 v7, 2, v4
	v_lshlrev_b32_e32 v8, 2, v8
	v_lshlrev_b32_e32 v9, 2, v9
	v_lshlrev_b32_e32 v10, 2, v10
	v_lshlrev_b32_e32 v12, 2, v12
	v_lshlrev_b32_e32 v14, 2, v14
	v_lshlrev_b32_e32 v15, 2, v15
	v_lshlrev_b32_e32 v16, 2, v16
	v_lshlrev_b32_e32 v17, 2, v17
	v_lshlrev_b32_e32 v178, 2, v178
	v_lshlrev_b32_e32 v11, 2, v11
	ds_bpermute_b32 v4, v7, v181
	ds_bpermute_b32 v5, v7, v181 offset:4
	ds_bpermute_b32 v6, v7, v181 offset:8
	ds_bpermute_b32 v7, v7, v181 offset:12
	ds_bpermute_b32 v8, v8, v181
	ds_bpermute_b32 v9, v9, v181
	ds_bpermute_b32 v10, v10, v181
	ds_bpermute_b32 v12, v12, v181
	ds_bpermute_b32 v14, v14, v181
	ds_bpermute_b32 v16, v16, v181
	ds_bpermute_b32 v178, v178, v181
	ds_bpermute_b32 v179, v11, v181
	ds_bpermute_b32 v17, v17, v181
	ds_bpermute_b32 v15, v15, v181
	ds_bpermute_b32 v13, v183, v181
	ds_bpermute_b32 v11, v182, v181
	s_waitcnt lgkmcnt(0)
	v_pk_mul_f32 v[128:129], v[128:129], v[178:179]
	v_pk_mul_f32 v[126:127], v[126:127], v[16:17]
	v_pk_mul_f32 v[124:125], v[124:125], v[14:15]
	v_pk_mul_f32 v[122:123], v[122:123], v[12:13]
	v_pk_mul_f32 v[120:121], v[120:121], v[10:11]
	v_pk_mul_f32 v[118:119], v[118:119], v[8:9]
	v_pk_mul_f32 v[116:117], v[116:117], v[6:7]
	v_pk_mul_f32 v[114:115], v[114:115], v[4:5]
	v_pk_mul_f32 v[112:113], v[112:113], v[178:179]
	v_pk_mul_f32 v[110:111], v[110:111], v[16:17]
	v_pk_mul_f32 v[108:109], v[108:109], v[14:15]
	v_pk_mul_f32 v[106:107], v[106:107], v[12:13]
	v_pk_mul_f32 v[104:105], v[104:105], v[10:11]
	v_pk_mul_f32 v[102:103], v[102:103], v[8:9]
	v_pk_mul_f32 v[100:101], v[100:101], v[6:7]
	v_pk_mul_f32 v[98:99], v[98:99], v[4:5]
	v_pk_mul_f32 v[144:145], v[144:145], v[178:179]
	v_pk_mul_f32 v[142:143], v[142:143], v[16:17]
	v_pk_mul_f32 v[140:141], v[140:141], v[14:15]
	v_pk_mul_f32 v[138:139], v[138:139], v[12:13]
	v_pk_mul_f32 v[136:137], v[136:137], v[10:11]
	v_pk_mul_f32 v[134:135], v[134:135], v[8:9]
	v_pk_mul_f32 v[132:133], v[132:133], v[6:7]
	v_pk_mul_f32 v[130:131], v[130:131], v[4:5]
	v_pk_mul_f32 v[96:97], v[96:97], v[178:179]
	v_pk_mul_f32 v[94:95], v[94:95], v[16:17]
	v_pk_mul_f32 v[92:93], v[92:93], v[14:15]
	v_pk_mul_f32 v[90:91], v[90:91], v[12:13]
	v_pk_mul_f32 v[88:89], v[88:89], v[10:11]
	v_pk_mul_f32 v[86:87], v[86:87], v[8:9]
	v_pk_mul_f32 v[84:85], v[84:85], v[6:7]
	v_pk_mul_f32 v[82:83], v[82:83], v[4:5]
	v_pk_mul_f32 v[80:81], v[80:81], v[178:179]
	v_pk_mul_f32 v[78:79], v[78:79], v[16:17]
	v_pk_mul_f32 v[76:77], v[76:77], v[14:15]
	v_pk_mul_f32 v[74:75], v[74:75], v[12:13]
	v_pk_mul_f32 v[72:73], v[72:73], v[10:11]
	v_pk_mul_f32 v[70:71], v[70:71], v[8:9]
	v_pk_mul_f32 v[68:69], v[68:69], v[6:7]
	v_pk_mul_f32 v[66:67], v[66:67], v[4:5]
	v_pk_mul_f32 v[64:65], v[64:65], v[178:179]
	v_pk_mul_f32 v[62:63], v[62:63], v[16:17]
	v_pk_mul_f32 v[60:61], v[60:61], v[14:15]
	v_pk_mul_f32 v[58:59], v[58:59], v[12:13]
	v_pk_mul_f32 v[56:57], v[56:57], v[10:11]
	v_pk_mul_f32 v[54:55], v[54:55], v[8:9]
	v_pk_mul_f32 v[52:53], v[52:53], v[6:7]
	v_pk_mul_f32 v[50:51], v[50:51], v[4:5]
	v_pk_mul_f32 v[48:49], v[48:49], v[178:179]
	v_pk_mul_f32 v[46:47], v[46:47], v[16:17]
	v_pk_mul_f32 v[44:45], v[44:45], v[14:15]
	v_pk_mul_f32 v[42:43], v[42:43], v[12:13]
	v_pk_mul_f32 v[40:41], v[40:41], v[10:11]
	v_pk_mul_f32 v[38:39], v[38:39], v[8:9]
	v_pk_mul_f32 v[36:37], v[36:37], v[6:7]
	v_pk_mul_f32 v[34:35], v[34:35], v[4:5]
	v_pk_mul_f32 v[32:33], v[32:33], v[178:179]
	v_pk_mul_f32 v[30:31], v[30:31], v[16:17]
	v_pk_mul_f32 v[28:29], v[28:29], v[14:15]
	v_pk_mul_f32 v[26:27], v[26:27], v[12:13]
	v_pk_mul_f32 v[24:25], v[24:25], v[10:11]
	v_pk_mul_f32 v[22:23], v[22:23], v[8:9]
	v_pk_mul_f32 v[20:21], v[20:21], v[6:7]
	v_pk_mul_f32 v[18:19], v[18:19], v[4:5]
	v_mul_f32_e32 v250, v250, v181
	v_mov_b32_e32 v251, v180
.LBB0_2772:
	s_and_b64 vcc, exec, s[10:11]
	s_cbranch_vccnz .LBB0_2777
	s_branch .LBB0_2776

.LBB0_2777:
	v_sub_f32_e32 v4, v253, v251
	s_mov_b32 s8, 0x3e0293ee
	v_pk_fma_f32 v[194:195], v[162:163], s[8:9], v[4:5] op_sel_hi:[1,0,0]
	v_pk_fma_f32 v[178:179], v[146:147], s[8:9], v[4:5] op_sel_hi:[1,0,0]
	v_exp_f32_e32 v194, v194
	v_exp_f32_e32 v195, v195
	v_exp_f32_e32 v178, v178
	v_exp_f32_e32 v179, v179
	v_pk_fma_f32 v[196:197], v[164:165], s[8:9], v[4:5] op_sel_hi:[1,0,0]
	v_pk_fma_f32 v[180:181], v[148:149], s[8:9], v[4:5] op_sel_hi:[1,0,0]
	v_pk_add_f32 v[6:7], v[194:195], v[178:179]
	v_exp_f32_e32 v196, v196
	v_exp_f32_e32 v197, v197
	v_exp_f32_e32 v180, v180
	v_exp_f32_e32 v181, v181
	v_pk_fma_f32 v[198:199], v[166:167], s[8:9], v[4:5] op_sel_hi:[1,0,0]
	v_pk_fma_f32 v[182:183], v[150:151], s[8:9], v[4:5] op_sel_hi:[1,0,0]
	v_pk_add_f32 v[6:7], v[6:7], v[196:197]
	v_pk_add_f32 v[6:7], v[6:7], v[180:181]
	v_exp_f32_e32 v198, v198
	v_exp_f32_e32 v199, v199
	v_exp_f32_e32 v182, v182
	v_exp_f32_e32 v183, v183
	v_pk_fma_f32 v[200:201], v[168:169], s[8:9], v[4:5] op_sel_hi:[1,0,0]
	v_pk_fma_f32 v[184:185], v[152:153], s[8:9], v[4:5] op_sel_hi:[1,0,0]
	v_pk_add_f32 v[6:7], v[6:7], v[198:199]
	v_pk_add_f32 v[6:7], v[6:7], v[182:183]
	v_exp_f32_e32 v200, v200
	v_exp_f32_e32 v201, v201
	v_exp_f32_e32 v184, v184
	v_exp_f32_e32 v185, v185
	v_pk_fma_f32 v[202:203], v[170:171], s[8:9], v[4:5] op_sel_hi:[1,0,0]
	v_pk_fma_f32 v[186:187], v[154:155], s[8:9], v[4:5] op_sel_hi:[1,0,0]
	v_pk_add_f32 v[6:7], v[6:7], v[200:201]
	v_pk_add_f32 v[6:7], v[6:7], v[184:185]
	v_exp_f32_e32 v202, v202
	v_exp_f32_e32 v203, v203
	v_exp_f32_e32 v186, v186
	v_exp_f32_e32 v187, v187
	v_pk_fma_f32 v[204:205], v[172:173], s[8:9], v[4:5] op_sel_hi:[1,0,0]
	v_pk_fma_f32 v[188:189], v[156:157], s[8:9], v[4:5] op_sel_hi:[1,0,0]
	v_pk_add_f32 v[6:7], v[6:7], v[202:203]
	v_pk_add_f32 v[6:7], v[6:7], v[186:187]
	v_exp_f32_e32 v204, v204
	v_exp_f32_e32 v205, v205
	v_exp_f32_e32 v188, v188
	v_exp_f32_e32 v189, v189
	v_pk_fma_f32 v[206:207], v[174:175], s[8:9], v[4:5] op_sel_hi:[1,0,0]
	v_pk_fma_f32 v[190:191], v[158:159], s[8:9], v[4:5] op_sel_hi:[1,0,0]
	v_pk_add_f32 v[6:7], v[6:7], v[204:205]
	v_pk_add_f32 v[6:7], v[6:7], v[188:189]
	v_exp_f32_e32 v206, v206
	v_exp_f32_e32 v207, v207
	v_exp_f32_e32 v190, v190
	v_exp_f32_e32 v191, v191
	v_pk_fma_f32 v[208:209], v[176:177], s[8:9], v[4:5] op_sel_hi:[1,0,0]
	v_fmamk_f32 v2, v160, 0x3e0293ee, v4
	v_pk_add_f32 v[6:7], v[6:7], v[206:207]
	v_pk_add_f32 v[6:7], v[6:7], v[190:191]
	v_exp_f32_e32 v208, v208
	v_exp_f32_e32 v209, v209
	v_exp_f32_e32 v192, v2
	v_fmac_f32_e32 v4, 0x3e0293ee, v161
	v_add_f32_e32 v7, v6, v7
	v_add_f32_e32 v7, v7, v208
	v_add_f32_e32 v7, v7, v192
	s_add_i32 s19, s19, 1
	s_branch .LBB0_2759
